# EpiRes<0> epilogues (q=8, q=10a): the 16 in-place residual loads of a tile requested up front instead of vmcnt(0) after each one
# speedup vs baseline: 1.0081x; 1.0003x over previous
; #define LAS __attribute__((address_space(3)))
; __device__ __forceinline__ unsigned cvt_pk_bf16(float lo, float hi) { f32x2_t v = {lo, hi}; bf16x2_t b = __builtin_convertvector(v, bf16x2_t); return __builtin_bit_cast(unsigned, b); }
; __device__ __forceinline__ float bflo(unsigned w) { return __uint_as_float(w << 16); }
; __device__ __forceinline__ float bfhi(unsigned w) { return __uint_as_float(w & 0xffff0000u); }
;     __device__ __forceinline__ void operator()(AccRef acc, const pg8::Unit& u, int, int, int, int) const {
;     ...
;         for (int ai = 0; ai < 2; ++ai)
; #pragma unroll
;             for (int m = 0; m < 4; ++m) {
;                 const int row = row0 + ai * 128 + m * 16; float ss = 0.f; float rs = 1.f;
;                 if (MODE == 1) rs = ((const LAS float*)((LAS unsigned char*)g_lds + pg8::RSL_OFF))[wid * 128 + ai * 64 + m * 16 + fr];
; #pragma unroll
;                 for (int bj = 0; bj < 2; ++bj) {
;                     const size_t off = (size_t)row * DM + col0 + bj * 128;
;                     f32x4 h0, h1; const f32x4 a0 = acc[ai][bj][m][0], a1 = acc[ai][bj][m][1];
;                     if (hin) { h0 = *(const f32x4*)(hin + off); h1 = *(const f32x4*)(hin + off + 4); }
;                     else { const v4u hw = *(const v4u*)(hinb + off); h0 = (f32x4){bflo(hw.x), bfhi(hw.x), bflo(hw.y), bfhi(hw.y)}; h1 = (f32x4){bflo(hw.z), bfhi(hw.z), bflo(hw.w), bfhi(hw.w)}; }
;                     if (MODE == 0) { h0 = h0 + a0 * alpha; h1 = h1 + a1 * alpha; }
;                     else { const v4u pw = *(const v4u*)(pp + off);
;                         h0[0] += sigm(a0[0] * rs) * bflo(pw.x); h0[1] += sigm(a0[1] * rs) * bfhi(pw.x); h0[2] += sigm(a0[2] * rs) * bflo(pw.y); h0[3] += sigm(a0[3] * rs) * bfhi(pw.y);
;                         h1[0] += sigm(a1[0] * rs) * bflo(pw.z); h1[1] += sigm(a1[1] * rs) * bfhi(pw.z); h1[2] += sigm(a1[2] * rs) * bflo(pw.w); h1[3] += sigm(a1[3] * rs) * bfhi(pw.w); }
;                     if (hout) { *(f32x4*)(hout + off) = h0; *(f32x4*)(hout + off + 4) = h1; }
;                     if (hb) { v4u w; w.x = cvt_pk_bf16(h0[0], h0[1]); w.y = cvt_pk_bf16(h0[2], h0[3]); w.z = cvt_pk_bf16(h1[0], h1[1]); w.w = cvt_pk_bf16(h1[2], h1[3]); *(v4u*)(hb + off) = w; }
;                     ss += ((h0[0] * h0[0] + h0[1] * h0[1]) + (h0[2] * h0[2] + h0[3] * h0[3])) + ((h1[0] * h1[0] + h1[1] * h1[1]) + (h1[2] * h1[2] + h1[3] * h1[3])); }
.LBB0_219:
	v_mov_b32_e32 v141, v155
	s_lshl_b32 s11, s40, 8
	v_readfirstlane_b32 s10, v141
	s_bfe_u32 s41, s10, 0x20006
	s_ashr_i32 s10, s10, 2
	v_bfe_u32 v148, v141, 4, 2
	s_andn2_b32 s10, s10, 63
	s_lshl_b32 s12, s4, 8
	s_lshl_b32 s13, s41, 5
	v_and_or_b32 v141, v141, 15, s11
	s_or_b32 s12, s13, s12
	v_add_u32_e32 v142, s10, v141
	v_lshl_or_b32 v140, v148, 3, s12
	v_ashrrev_i32_e32 v143, 31, v142
	v_ashrrev_i32_e32 v141, 31, v140
	v_lshlrev_b64 v[144:145], 10, v[142:143]
	v_readlane_b32 s10, v254, 45
	v_lshl_add_u64 v[144:145], v[144:145], 0, v[140:141]
	v_readlane_b32 s11, v254, 46
	v_cndmask_b32_e64 v149, 0, 1, s[16:17]
	s_andn2_b64 vcc, exec, s[16:17]
	v_lshl_add_u64 v[144:145], v[144:145], 1, s[10:11]
	global_load_dwordx4 v[180:183], v[144:145], off
	global_load_dwordx4 v[184:187], v[144:145], off offset:256
	v_add_co_u32_e32 v246, vcc, 0x8000, v144
	s_nop 1
	v_addc_co_u32_e32 v247, vcc, 0, v145, vcc
	global_load_dwordx4 v[188:191], v[246:247], off
	global_load_dwordx4 v[192:195], v[246:247], off offset:256
	v_add_co_u32_e32 v244, vcc, 0x10000, v144
	s_nop 1
	v_addc_co_u32_e32 v245, vcc, 0, v145, vcc
	global_load_dwordx4 v[196:199], v[244:245], off
	global_load_dwordx4 v[200:203], v[244:245], off offset:256
	v_add_co_u32_e32 v246, vcc, 0x18000, v144
	s_nop 1
	v_addc_co_u32_e32 v247, vcc, 0, v145, vcc
	global_load_dwordx4 v[204:207], v[246:247], off
	global_load_dwordx4 v[208:211], v[246:247], off offset:256
	v_add_co_u32_e32 v244, vcc, 0x40000, v144
	s_nop 1
	v_addc_co_u32_e32 v245, vcc, 0, v145, vcc
	global_load_dwordx4 v[212:215], v[244:245], off
	global_load_dwordx4 v[216:219], v[244:245], off offset:256
	v_add_co_u32_e32 v246, vcc, 0x48000, v144
	s_nop 1
	v_addc_co_u32_e32 v247, vcc, 0, v145, vcc
	global_load_dwordx4 v[220:223], v[246:247], off
	global_load_dwordx4 v[224:227], v[246:247], off offset:256
	v_add_co_u32_e32 v244, vcc, 0x50000, v144
	s_nop 1
	v_addc_co_u32_e32 v245, vcc, 0, v145, vcc
	global_load_dwordx4 v[228:231], v[244:245], off
	global_load_dwordx4 v[232:235], v[244:245], off offset:256
	v_add_co_u32_e32 v246, vcc, 0x58000, v144
	s_nop 1
	v_addc_co_u32_e32 v247, vcc, 0, v145, vcc
	global_load_dwordx4 v[236:239], v[246:247], off
	global_load_dwordx4 v[240:243], v[246:247], off offset:256
	s_waitcnt vmcnt(0)
	v_cmp_ne_u32_e64 s[10:11], 1, v149
	v_lshlrev_b32_e32 v156, 16, v180
	v_and_b32_e32 v157, 0xffff0000, v180
	v_lshlrev_b32_e32 v150, 16, v181
	v_and_b32_e32 v151, 0xffff0000, v181
	v_lshlrev_b32_e32 v158, 16, v182
	v_and_b32_e32 v159, 0xffff0000, v182
	v_lshlrev_b32_e32 v152, 16, v183
	v_and_b32_e32 v153, 0xffff0000, v183
	v_pk_fma_f32 v[128:129], v[128:129], 0.5, v[150:151] op_sel_hi:[1,0,1]
	v_pk_fma_f32 v[126:127], v[126:127], 0.5, v[156:157] op_sel_hi:[1,0,1]
	v_pk_fma_f32 v[124:125], v[124:125], 0.5, v[152:153] op_sel_hi:[1,0,1]
	v_pk_fma_f32 v[122:123], v[122:123], 0.5, v[158:159] op_sel_hi:[1,0,1]
	s_cbranch_vccnz .LBB0_221
	v_cvt_pk_bf16_f32 v150, v126, v127
	v_cvt_pk_bf16_f32 v151, v128, v129
	v_cvt_pk_bf16_f32 v152, v122, v123
	v_cvt_pk_bf16_f32 v153, v124, v125
	global_store_dwordx4 v[144:145], v[150:153], off
.LBB0_221:
	s_and_b64 vcc, exec, s[10:11]
	v_lshlrev_b32_e32 v156, 16, v184
	v_and_b32_e32 v157, 0xffff0000, v184
	v_lshlrev_b32_e32 v150, 16, v185
	v_and_b32_e32 v151, 0xffff0000, v185
	v_lshlrev_b32_e32 v158, 16, v186
	v_and_b32_e32 v159, 0xffff0000, v186
	v_lshlrev_b32_e32 v152, 16, v187
	v_and_b32_e32 v153, 0xffff0000, v187
	v_pk_fma_f32 v[120:121], v[120:121], 0.5, v[150:151] op_sel_hi:[1,0,1]
	v_pk_fma_f32 v[118:119], v[118:119], 0.5, v[156:157] op_sel_hi:[1,0,1]
	v_pk_fma_f32 v[116:117], v[116:117], 0.5, v[152:153] op_sel_hi:[1,0,1]
	v_pk_fma_f32 v[114:115], v[114:115], 0.5, v[158:159] op_sel_hi:[1,0,1]
	s_cbranch_vccnz .LBB0_223
	v_cvt_pk_bf16_f32 v150, v118, v119
	v_cvt_pk_bf16_f32 v151, v120, v121
	v_cvt_pk_bf16_f32 v152, v114, v115
	v_cvt_pk_bf16_f32 v153, v116, v117
	global_store_dwordx4 v[144:145], v[150:153], off offset:256

; __device__ __forceinline__ unsigned cvt_pk_bf16(float lo, float hi) { f32x2_t v = {lo, hi}; bf16x2_t b = __builtin_convertvector(v, bf16x2_t); return __builtin_bit_cast(unsigned, b); }
; __device__ __forceinline__ float bflo(unsigned w) { return __uint_as_float(w << 16); }
; __device__ __forceinline__ float bfhi(unsigned w) { return __uint_as_float(w & 0xffff0000u); }
; __device__ __forceinline__ float sigm(float x) { return __builtin_amdgcn_rcpf(1.0f + __expf(-x)); }
;     __device__ __forceinline__ void operator()(AccRef acc, const pg8::Unit& u, int, int, int, int) const {
;     ...
;                 for (int bj = 0; bj < 2; ++bj) {
;                     const size_t off = (size_t)row * DM + col0 + bj * 128;
;                     f32x4 h0, h1; const f32x4 a0 = acc[ai][bj][m][0], a1 = acc[ai][bj][m][1];
;                     if (hin) { h0 = *(const f32x4*)(hin + off); h1 = *(const f32x4*)(hin + off + 4); }
;                     else { const v4u hw = *(const v4u*)(hinb + off); h0 = (f32x4){bflo(hw.x), bfhi(hw.x), bflo(hw.y), bfhi(hw.y)}; h1 = (f32x4){bflo(hw.z), bfhi(hw.z), bflo(hw.w), bfhi(hw.w)}; }
;                     if (MODE == 0) { h0 = h0 + a0 * alpha; h1 = h1 + a1 * alpha; }
;                     else { const v4u pw = *(const v4u*)(pp + off);
;                         h0[0] += sigm(a0[0] * rs) * bflo(pw.x); h0[1] += sigm(a0[1] * rs) * bfhi(pw.x); h0[2] += sigm(a0[2] * rs) * bflo(pw.y); h0[3] += sigm(a0[3] * rs) * bfhi(pw.y);
;                         h1[0] += sigm(a1[0] * rs) * bflo(pw.z); h1[1] += sigm(a1[1] * rs) * bfhi(pw.z); h1[2] += sigm(a1[2] * rs) * bflo(pw.w); h1[3] += sigm(a1[3] * rs) * bfhi(pw.w); }
;                     if (hout) { *(f32x4*)(hout + off) = h0; *(f32x4*)(hout + off + 4) = h1; }
;                     if (hb) { v4u w; w.x = cvt_pk_bf16(h0[0], h0[1]); w.y = cvt_pk_bf16(h0[2], h0[3]); w.z = cvt_pk_bf16(h1[0], h1[1]); w.w = cvt_pk_bf16(h1[2], h1[3]); *(v4u*)(hb + off) = w; }
.LBB0_225:
	s_or_b64 exec, exec, s[24:25]
	v_or_b32_e32 v114, 16, v142
	s_waitcnt lgkmcnt(0)
	v_ashrrev_i32_e32 v115, 31, v114
	v_lshlrev_b64 v[116:117], 10, v[114:115]
	v_readlane_b32 s4, v254, 45
	v_lshl_add_u64 v[116:117], v[116:117], 0, v[140:141]
	v_readlane_b32 s5, v254, 46
	s_and_b64 vcc, exec, s[10:11]
	s_nop 0
	v_lshl_add_u64 v[116:117], v[116:117], 1, s[4:5]
	v_lshlrev_b32_e32 v120, 16, v188
	v_and_b32_e32 v121, 0xffff0000, v188
	v_lshlrev_b32_e32 v124, 16, v189
	v_and_b32_e32 v125, 0xffff0000, v189
	v_lshlrev_b32_e32 v128, 16, v190
	v_and_b32_e32 v129, 0xffff0000, v190
	v_lshlrev_b32_e32 v126, 16, v191
	v_and_b32_e32 v127, 0xffff0000, v191
	v_pk_fma_f32 v[112:113], v[112:113], 0.5, v[124:125] op_sel_hi:[1,0,1]
	v_pk_fma_f32 v[110:111], v[110:111], 0.5, v[120:121] op_sel_hi:[1,0,1]
	v_pk_fma_f32 v[108:109], v[108:109], 0.5, v[126:127] op_sel_hi:[1,0,1]
	v_pk_fma_f32 v[106:107], v[106:107], 0.5, v[128:129] op_sel_hi:[1,0,1]
	s_cbranch_vccnz .LBB0_227
	v_cvt_pk_bf16_f32 v124, v110, v111
	v_cvt_pk_bf16_f32 v125, v112, v113
	v_cvt_pk_bf16_f32 v126, v106, v107
	v_cvt_pk_bf16_f32 v127, v108, v109
	global_store_dwordx4 v[116:117], v[124:127], off
.LBB0_227:
	s_and_b64 vcc, exec, s[10:11]
	v_lshlrev_b32_e32 v120, 16, v192
	v_and_b32_e32 v121, 0xffff0000, v192
	v_lshlrev_b32_e32 v124, 16, v193
	v_and_b32_e32 v125, 0xffff0000, v193
	v_lshlrev_b32_e32 v128, 16, v194
	v_and_b32_e32 v129, 0xffff0000, v194
	v_lshlrev_b32_e32 v126, 16, v195
	v_and_b32_e32 v127, 0xffff0000, v195
	v_pk_fma_f32 v[104:105], v[104:105], 0.5, v[124:125] op_sel_hi:[1,0,1]
	v_pk_fma_f32 v[102:103], v[102:103], 0.5, v[120:121] op_sel_hi:[1,0,1]
	v_pk_fma_f32 v[100:101], v[100:101], 0.5, v[126:127] op_sel_hi:[1,0,1]
	v_pk_fma_f32 v[98:99], v[98:99], 0.5, v[128:129] op_sel_hi:[1,0,1]
	s_cbranch_vccnz .LBB0_229
	v_cvt_pk_bf16_f32 v124, v102, v103
	v_cvt_pk_bf16_f32 v125, v104, v105
	v_cvt_pk_bf16_f32 v126, v98, v99
	v_cvt_pk_bf16_f32 v127, v100, v101
	global_store_dwordx4 v[116:117], v[124:127], off offset:256

; __device__ __forceinline__ unsigned cvt_pk_bf16(float lo, float hi) { f32x2_t v = {lo, hi}; bf16x2_t b = __builtin_convertvector(v, bf16x2_t); return __builtin_bit_cast(unsigned, b); }
; __device__ __forceinline__ float bflo(unsigned w) { return __uint_as_float(w << 16); }
; __device__ __forceinline__ float bfhi(unsigned w) { return __uint_as_float(w & 0xffff0000u); }
; __device__ __forceinline__ float sigm(float x) { return __builtin_amdgcn_rcpf(1.0f + __expf(-x)); }
;     __device__ __forceinline__ void operator()(AccRef acc, const pg8::Unit& u, int, int, int, int) const {
;     ...
;                 for (int bj = 0; bj < 2; ++bj) {
;                     const size_t off = (size_t)row * DM + col0 + bj * 128;
;                     f32x4 h0, h1; const f32x4 a0 = acc[ai][bj][m][0], a1 = acc[ai][bj][m][1];
;                     if (hin) { h0 = *(const f32x4*)(hin + off); h1 = *(const f32x4*)(hin + off + 4); }
;                     else { const v4u hw = *(const v4u*)(hinb + off); h0 = (f32x4){bflo(hw.x), bfhi(hw.x), bflo(hw.y), bfhi(hw.y)}; h1 = (f32x4){bflo(hw.z), bfhi(hw.z), bflo(hw.w), bfhi(hw.w)}; }
;                     if (MODE == 0) { h0 = h0 + a0 * alpha; h1 = h1 + a1 * alpha; }
;                     else { const v4u pw = *(const v4u*)(pp + off);
;                         h0[0] += sigm(a0[0] * rs) * bflo(pw.x); h0[1] += sigm(a0[1] * rs) * bfhi(pw.x); h0[2] += sigm(a0[2] * rs) * bflo(pw.y); h0[3] += sigm(a0[3] * rs) * bfhi(pw.y);
;                         h1[0] += sigm(a1[0] * rs) * bflo(pw.z); h1[1] += sigm(a1[1] * rs) * bfhi(pw.z); h1[2] += sigm(a1[2] * rs) * bflo(pw.w); h1[3] += sigm(a1[3] * rs) * bfhi(pw.w); }
;                     if (hout) { *(f32x4*)(hout + off) = h0; *(f32x4*)(hout + off + 4) = h1; }
;                     if (hb) { v4u w; w.x = cvt_pk_bf16(h0[0], h0[1]); w.y = cvt_pk_bf16(h0[2], h0[3]); w.z = cvt_pk_bf16(h1[0], h1[1]); w.w = cvt_pk_bf16(h1[2], h1[3]); *(v4u*)(hb + off) = w; }
.LBB0_231:
	s_or_b64 exec, exec, s[24:25]
	v_or_b32_e32 v98, 32, v142
	s_waitcnt lgkmcnt(0)
	v_ashrrev_i32_e32 v99, 31, v98
	v_lshlrev_b64 v[100:101], 10, v[98:99]
	v_readlane_b32 s4, v254, 45
	v_lshl_add_u64 v[100:101], v[100:101], 0, v[140:141]
	v_readlane_b32 s5, v254, 46
	s_and_b64 vcc, exec, s[10:11]
	s_nop 0
	v_lshl_add_u64 v[100:101], v[100:101], 1, s[4:5]
	v_lshlrev_b32_e32 v106, 16, v196
	v_and_b32_e32 v107, 0xffff0000, v196
	v_lshlrev_b32_e32 v102, 16, v197
	v_and_b32_e32 v103, 0xffff0000, v197
	v_lshlrev_b32_e32 v108, 16, v198
	v_and_b32_e32 v109, 0xffff0000, v198
	v_lshlrev_b32_e32 v104, 16, v199
	v_and_b32_e32 v105, 0xffff0000, v199
	v_pk_fma_f32 v[96:97], v[96:97], 0.5, v[102:103] op_sel_hi:[1,0,1]
	v_pk_fma_f32 v[94:95], v[94:95], 0.5, v[106:107] op_sel_hi:[1,0,1]
	v_pk_fma_f32 v[92:93], v[92:93], 0.5, v[104:105] op_sel_hi:[1,0,1]
	v_pk_fma_f32 v[90:91], v[90:91], 0.5, v[108:109] op_sel_hi:[1,0,1]
	s_cbranch_vccnz .LBB0_233
	v_cvt_pk_bf16_f32 v102, v94, v95
	v_cvt_pk_bf16_f32 v103, v96, v97
	v_cvt_pk_bf16_f32 v104, v90, v91
	v_cvt_pk_bf16_f32 v105, v92, v93
	global_store_dwordx4 v[100:101], v[102:105], off
.LBB0_233:
	s_and_b64 vcc, exec, s[10:11]
	v_lshlrev_b32_e32 v106, 16, v200
	v_and_b32_e32 v107, 0xffff0000, v200
	v_lshlrev_b32_e32 v102, 16, v201
	v_and_b32_e32 v103, 0xffff0000, v201
	v_lshlrev_b32_e32 v108, 16, v202
	v_and_b32_e32 v109, 0xffff0000, v202
	v_lshlrev_b32_e32 v104, 16, v203
	v_and_b32_e32 v105, 0xffff0000, v203
	v_pk_fma_f32 v[88:89], v[88:89], 0.5, v[102:103] op_sel_hi:[1,0,1]
	v_pk_fma_f32 v[86:87], v[86:87], 0.5, v[106:107] op_sel_hi:[1,0,1]
	v_pk_fma_f32 v[84:85], v[84:85], 0.5, v[104:105] op_sel_hi:[1,0,1]
	v_pk_fma_f32 v[82:83], v[82:83], 0.5, v[108:109] op_sel_hi:[1,0,1]
	s_cbranch_vccnz .LBB0_235
	v_cvt_pk_bf16_f32 v102, v86, v87
	v_cvt_pk_bf16_f32 v103, v88, v89
	v_cvt_pk_bf16_f32 v104, v82, v83
	v_cvt_pk_bf16_f32 v105, v84, v85
	global_store_dwordx4 v[100:101], v[102:105], off offset:256

; __device__ __forceinline__ unsigned cvt_pk_bf16(float lo, float hi) { f32x2_t v = {lo, hi}; bf16x2_t b = __builtin_convertvector(v, bf16x2_t); return __builtin_bit_cast(unsigned, b); }
; __device__ __forceinline__ float bflo(unsigned w) { return __uint_as_float(w << 16); }
; __device__ __forceinline__ float bfhi(unsigned w) { return __uint_as_float(w & 0xffff0000u); }
; __device__ __forceinline__ float sigm(float x) { return __builtin_amdgcn_rcpf(1.0f + __expf(-x)); }
;     __device__ __forceinline__ void operator()(AccRef acc, const pg8::Unit& u, int, int, int, int) const {
;     ...
;                 for (int bj = 0; bj < 2; ++bj) {
;                     const size_t off = (size_t)row * DM + col0 + bj * 128;
;                     f32x4 h0, h1; const f32x4 a0 = acc[ai][bj][m][0], a1 = acc[ai][bj][m][1];
;                     if (hin) { h0 = *(const f32x4*)(hin + off); h1 = *(const f32x4*)(hin + off + 4); }
;                     else { const v4u hw = *(const v4u*)(hinb + off); h0 = (f32x4){bflo(hw.x), bfhi(hw.x), bflo(hw.y), bfhi(hw.y)}; h1 = (f32x4){bflo(hw.z), bfhi(hw.z), bflo(hw.w), bfhi(hw.w)}; }
;                     if (MODE == 0) { h0 = h0 + a0 * alpha; h1 = h1 + a1 * alpha; }
;                     else { const v4u pw = *(const v4u*)(pp + off);
;                         h0[0] += sigm(a0[0] * rs) * bflo(pw.x); h0[1] += sigm(a0[1] * rs) * bfhi(pw.x); h0[2] += sigm(a0[2] * rs) * bflo(pw.y); h0[3] += sigm(a0[3] * rs) * bfhi(pw.y);
;                         h1[0] += sigm(a1[0] * rs) * bflo(pw.z); h1[1] += sigm(a1[1] * rs) * bfhi(pw.z); h1[2] += sigm(a1[2] * rs) * bflo(pw.w); h1[3] += sigm(a1[3] * rs) * bfhi(pw.w); }
;                     if (hout) { *(f32x4*)(hout + off) = h0; *(f32x4*)(hout + off + 4) = h1; }
;                     if (hb) { v4u w; w.x = cvt_pk_bf16(h0[0], h0[1]); w.y = cvt_pk_bf16(h0[2], h0[3]); w.z = cvt_pk_bf16(h1[0], h1[1]); w.w = cvt_pk_bf16(h1[2], h1[3]); *(v4u*)(hb + off) = w; }
.LBB0_237:
	s_or_b64 exec, exec, s[24:25]
	v_or_b32_e32 v82, 48, v142
	s_waitcnt lgkmcnt(0)
	v_ashrrev_i32_e32 v83, 31, v82
	v_lshlrev_b64 v[84:85], 10, v[82:83]
	v_readlane_b32 s4, v254, 45
	v_lshl_add_u64 v[84:85], v[84:85], 0, v[140:141]
	v_readlane_b32 s5, v254, 46
	s_and_b64 vcc, exec, s[10:11]
	s_nop 0
	v_lshl_add_u64 v[84:85], v[84:85], 1, s[4:5]
	v_lshlrev_b32_e32 v90, 16, v204
	v_and_b32_e32 v91, 0xffff0000, v204
	v_lshlrev_b32_e32 v86, 16, v205
	v_and_b32_e32 v87, 0xffff0000, v205
	v_lshlrev_b32_e32 v92, 16, v206
	v_and_b32_e32 v93, 0xffff0000, v206
	v_lshlrev_b32_e32 v88, 16, v207
	v_and_b32_e32 v89, 0xffff0000, v207
	v_pk_fma_f32 v[80:81], v[80:81], 0.5, v[86:87] op_sel_hi:[1,0,1]
	v_pk_fma_f32 v[78:79], v[78:79], 0.5, v[90:91] op_sel_hi:[1,0,1]
	v_pk_fma_f32 v[76:77], v[76:77], 0.5, v[88:89] op_sel_hi:[1,0,1]
	v_pk_fma_f32 v[74:75], v[74:75], 0.5, v[92:93] op_sel_hi:[1,0,1]
	s_cbranch_vccnz .LBB0_239
	v_cvt_pk_bf16_f32 v86, v78, v79
	v_cvt_pk_bf16_f32 v87, v80, v81
	v_cvt_pk_bf16_f32 v88, v74, v75
	v_cvt_pk_bf16_f32 v89, v76, v77
	global_store_dwordx4 v[84:85], v[86:89], off
.LBB0_239:
	s_and_b64 vcc, exec, s[10:11]
	v_lshlrev_b32_e32 v90, 16, v208
	v_and_b32_e32 v91, 0xffff0000, v208
	v_lshlrev_b32_e32 v86, 16, v209
	v_and_b32_e32 v87, 0xffff0000, v209
	v_lshlrev_b32_e32 v92, 16, v210
	v_and_b32_e32 v93, 0xffff0000, v210
	v_lshlrev_b32_e32 v88, 16, v211
	v_and_b32_e32 v89, 0xffff0000, v211
	v_pk_fma_f32 v[72:73], v[72:73], 0.5, v[86:87] op_sel_hi:[1,0,1]
	v_pk_fma_f32 v[70:71], v[70:71], 0.5, v[90:91] op_sel_hi:[1,0,1]
	v_pk_fma_f32 v[68:69], v[68:69], 0.5, v[88:89] op_sel_hi:[1,0,1]
	v_pk_fma_f32 v[66:67], v[66:67], 0.5, v[92:93] op_sel_hi:[1,0,1]
	s_cbranch_vccnz .LBB0_241
	v_cvt_pk_bf16_f32 v86, v70, v71
	v_cvt_pk_bf16_f32 v87, v72, v73
	v_cvt_pk_bf16_f32 v88, v66, v67
	v_cvt_pk_bf16_f32 v89, v68, v69
	global_store_dwordx4 v[84:85], v[86:89], off offset:256

; __device__ __forceinline__ unsigned cvt_pk_bf16(float lo, float hi) { f32x2_t v = {lo, hi}; bf16x2_t b = __builtin_convertvector(v, bf16x2_t); return __builtin_bit_cast(unsigned, b); }
; __device__ __forceinline__ float bflo(unsigned w) { return __uint_as_float(w << 16); }
; __device__ __forceinline__ float bfhi(unsigned w) { return __uint_as_float(w & 0xffff0000u); }
; __device__ __forceinline__ float sigm(float x) { return __builtin_amdgcn_rcpf(1.0f + __expf(-x)); }
;     __device__ __forceinline__ void operator()(AccRef acc, const pg8::Unit& u, int, int, int, int) const {
;     ...
;                 for (int bj = 0; bj < 2; ++bj) {
;                     const size_t off = (size_t)row * DM + col0 + bj * 128;
;                     f32x4 h0, h1; const f32x4 a0 = acc[ai][bj][m][0], a1 = acc[ai][bj][m][1];
;                     if (hin) { h0 = *(const f32x4*)(hin + off); h1 = *(const f32x4*)(hin + off + 4); }
;                     else { const v4u hw = *(const v4u*)(hinb + off); h0 = (f32x4){bflo(hw.x), bfhi(hw.x), bflo(hw.y), bfhi(hw.y)}; h1 = (f32x4){bflo(hw.z), bfhi(hw.z), bflo(hw.w), bfhi(hw.w)}; }
;                     if (MODE == 0) { h0 = h0 + a0 * alpha; h1 = h1 + a1 * alpha; }
;                     else { const v4u pw = *(const v4u*)(pp + off);
;                         h0[0] += sigm(a0[0] * rs) * bflo(pw.x); h0[1] += sigm(a0[1] * rs) * bfhi(pw.x); h0[2] += sigm(a0[2] * rs) * bflo(pw.y); h0[3] += sigm(a0[3] * rs) * bfhi(pw.y);
;                         h1[0] += sigm(a1[0] * rs) * bflo(pw.z); h1[1] += sigm(a1[1] * rs) * bfhi(pw.z); h1[2] += sigm(a1[2] * rs) * bflo(pw.w); h1[3] += sigm(a1[3] * rs) * bfhi(pw.w); }
;                     if (hout) { *(f32x4*)(hout + off) = h0; *(f32x4*)(hout + off + 4) = h1; }
;                     if (hb) { v4u w; w.x = cvt_pk_bf16(h0[0], h0[1]); w.y = cvt_pk_bf16(h0[2], h0[3]); w.z = cvt_pk_bf16(h1[0], h1[1]); w.w = cvt_pk_bf16(h1[2], h1[3]); *(v4u*)(hb + off) = w; }
.LBB0_243:
	s_or_b64 exec, exec, s[24:25]
	v_add_u32_e32 v66, 0x80, v142
	s_waitcnt lgkmcnt(0)
	v_ashrrev_i32_e32 v67, 31, v66
	v_lshlrev_b64 v[68:69], 10, v[66:67]
	v_readlane_b32 s4, v254, 45
	v_lshl_add_u64 v[68:69], v[68:69], 0, v[140:141]
	v_readlane_b32 s5, v254, 46
	s_and_b64 vcc, exec, s[10:11]
	s_nop 0
	v_lshl_add_u64 v[68:69], v[68:69], 1, s[4:5]
	v_lshlrev_b32_e32 v74, 16, v212
	v_and_b32_e32 v75, 0xffff0000, v212
	v_lshlrev_b32_e32 v70, 16, v213
	v_and_b32_e32 v71, 0xffff0000, v213
	v_lshlrev_b32_e32 v76, 16, v214
	v_and_b32_e32 v77, 0xffff0000, v214
	v_lshlrev_b32_e32 v72, 16, v215
	v_and_b32_e32 v73, 0xffff0000, v215
	v_pk_fma_f32 v[64:65], v[64:65], 0.5, v[70:71] op_sel_hi:[1,0,1]
	v_pk_fma_f32 v[62:63], v[62:63], 0.5, v[74:75] op_sel_hi:[1,0,1]
	v_pk_fma_f32 v[60:61], v[60:61], 0.5, v[72:73] op_sel_hi:[1,0,1]
	v_pk_fma_f32 v[58:59], v[58:59], 0.5, v[76:77] op_sel_hi:[1,0,1]
	s_cbranch_vccnz .LBB0_245
	v_cvt_pk_bf16_f32 v70, v62, v63
	v_cvt_pk_bf16_f32 v71, v64, v65
	v_cvt_pk_bf16_f32 v72, v58, v59
	v_cvt_pk_bf16_f32 v73, v60, v61
	global_store_dwordx4 v[68:69], v[70:73], off
.LBB0_245:
	s_and_b64 vcc, exec, s[10:11]
	v_lshlrev_b32_e32 v74, 16, v216
	v_and_b32_e32 v75, 0xffff0000, v216
	v_lshlrev_b32_e32 v70, 16, v217
	v_and_b32_e32 v71, 0xffff0000, v217
	v_lshlrev_b32_e32 v76, 16, v218
	v_and_b32_e32 v77, 0xffff0000, v218
	v_lshlrev_b32_e32 v72, 16, v219
	v_and_b32_e32 v73, 0xffff0000, v219
	v_pk_fma_f32 v[56:57], v[56:57], 0.5, v[70:71] op_sel_hi:[1,0,1]
	v_pk_fma_f32 v[54:55], v[54:55], 0.5, v[74:75] op_sel_hi:[1,0,1]
	v_pk_fma_f32 v[52:53], v[52:53], 0.5, v[72:73] op_sel_hi:[1,0,1]
	v_pk_fma_f32 v[50:51], v[50:51], 0.5, v[76:77] op_sel_hi:[1,0,1]
	s_cbranch_vccnz .LBB0_247
	v_cvt_pk_bf16_f32 v70, v54, v55
	v_cvt_pk_bf16_f32 v71, v56, v57
	v_cvt_pk_bf16_f32 v72, v50, v51
	v_cvt_pk_bf16_f32 v73, v52, v53
	global_store_dwordx4 v[68:69], v[70:73], off offset:256

; __device__ __forceinline__ unsigned cvt_pk_bf16(float lo, float hi) { f32x2_t v = {lo, hi}; bf16x2_t b = __builtin_convertvector(v, bf16x2_t); return __builtin_bit_cast(unsigned, b); }
; __device__ __forceinline__ float bflo(unsigned w) { return __uint_as_float(w << 16); }
; __device__ __forceinline__ float bfhi(unsigned w) { return __uint_as_float(w & 0xffff0000u); }
; __device__ __forceinline__ float sigm(float x) { return __builtin_amdgcn_rcpf(1.0f + __expf(-x)); }
;     __device__ __forceinline__ void operator()(AccRef acc, const pg8::Unit& u, int, int, int, int) const {
;     ...
;                 for (int bj = 0; bj < 2; ++bj) {
;                     const size_t off = (size_t)row * DM + col0 + bj * 128;
;                     f32x4 h0, h1; const f32x4 a0 = acc[ai][bj][m][0], a1 = acc[ai][bj][m][1];
;                     if (hin) { h0 = *(const f32x4*)(hin + off); h1 = *(const f32x4*)(hin + off + 4); }
;                     else { const v4u hw = *(const v4u*)(hinb + off); h0 = (f32x4){bflo(hw.x), bfhi(hw.x), bflo(hw.y), bfhi(hw.y)}; h1 = (f32x4){bflo(hw.z), bfhi(hw.z), bflo(hw.w), bfhi(hw.w)}; }
;                     if (MODE == 0) { h0 = h0 + a0 * alpha; h1 = h1 + a1 * alpha; }
;                     else { const v4u pw = *(const v4u*)(pp + off);
;                         h0[0] += sigm(a0[0] * rs) * bflo(pw.x); h0[1] += sigm(a0[1] * rs) * bfhi(pw.x); h0[2] += sigm(a0[2] * rs) * bflo(pw.y); h0[3] += sigm(a0[3] * rs) * bfhi(pw.y);
;                         h1[0] += sigm(a1[0] * rs) * bflo(pw.z); h1[1] += sigm(a1[1] * rs) * bfhi(pw.z); h1[2] += sigm(a1[2] * rs) * bflo(pw.w); h1[3] += sigm(a1[3] * rs) * bfhi(pw.w); }
;                     if (hout) { *(f32x4*)(hout + off) = h0; *(f32x4*)(hout + off + 4) = h1; }
;                     if (hb) { v4u w; w.x = cvt_pk_bf16(h0[0], h0[1]); w.y = cvt_pk_bf16(h0[2], h0[3]); w.z = cvt_pk_bf16(h1[0], h1[1]); w.w = cvt_pk_bf16(h1[2], h1[3]); *(v4u*)(hb + off) = w; }
.LBB0_249:
	s_or_b64 exec, exec, s[24:25]
	v_add_u32_e32 v50, 0x90, v142
	s_waitcnt lgkmcnt(0)
	v_ashrrev_i32_e32 v51, 31, v50
	v_lshlrev_b64 v[52:53], 10, v[50:51]
	v_readlane_b32 s4, v254, 45
	v_lshl_add_u64 v[52:53], v[52:53], 0, v[140:141]
	v_readlane_b32 s5, v254, 46
	s_and_b64 vcc, exec, s[10:11]
	s_nop 0
	v_lshl_add_u64 v[52:53], v[52:53], 1, s[4:5]
	v_lshlrev_b32_e32 v58, 16, v220
	v_and_b32_e32 v59, 0xffff0000, v220
	v_lshlrev_b32_e32 v54, 16, v221
	v_and_b32_e32 v55, 0xffff0000, v221
	v_lshlrev_b32_e32 v60, 16, v222
	v_and_b32_e32 v61, 0xffff0000, v222
	v_lshlrev_b32_e32 v56, 16, v223
	v_and_b32_e32 v57, 0xffff0000, v223
	v_pk_fma_f32 v[48:49], v[48:49], 0.5, v[54:55] op_sel_hi:[1,0,1]
	v_pk_fma_f32 v[46:47], v[46:47], 0.5, v[58:59] op_sel_hi:[1,0,1]
	v_pk_fma_f32 v[44:45], v[44:45], 0.5, v[56:57] op_sel_hi:[1,0,1]
	v_pk_fma_f32 v[42:43], v[42:43], 0.5, v[60:61] op_sel_hi:[1,0,1]
	s_cbranch_vccnz .LBB0_251
	v_cvt_pk_bf16_f32 v54, v46, v47
	v_cvt_pk_bf16_f32 v55, v48, v49
	v_cvt_pk_bf16_f32 v56, v42, v43
	v_cvt_pk_bf16_f32 v57, v44, v45
	global_store_dwordx4 v[52:53], v[54:57], off
.LBB0_251:
	s_and_b64 vcc, exec, s[10:11]
	v_lshlrev_b32_e32 v58, 16, v224
	v_and_b32_e32 v59, 0xffff0000, v224
	v_lshlrev_b32_e32 v54, 16, v225
	v_and_b32_e32 v55, 0xffff0000, v225
	v_lshlrev_b32_e32 v60, 16, v226
	v_and_b32_e32 v61, 0xffff0000, v226
	v_lshlrev_b32_e32 v56, 16, v227
	v_and_b32_e32 v57, 0xffff0000, v227
	v_pk_fma_f32 v[40:41], v[40:41], 0.5, v[54:55] op_sel_hi:[1,0,1]
	v_pk_fma_f32 v[38:39], v[38:39], 0.5, v[58:59] op_sel_hi:[1,0,1]
	v_pk_fma_f32 v[36:37], v[36:37], 0.5, v[56:57] op_sel_hi:[1,0,1]
	v_pk_fma_f32 v[34:35], v[34:35], 0.5, v[60:61] op_sel_hi:[1,0,1]
	s_cbranch_vccnz .LBB0_253
	v_cvt_pk_bf16_f32 v54, v38, v39
	v_cvt_pk_bf16_f32 v55, v40, v41
	v_cvt_pk_bf16_f32 v56, v34, v35
	v_cvt_pk_bf16_f32 v57, v36, v37
	global_store_dwordx4 v[52:53], v[54:57], off offset:256

; __device__ __forceinline__ unsigned cvt_pk_bf16(float lo, float hi) { f32x2_t v = {lo, hi}; bf16x2_t b = __builtin_convertvector(v, bf16x2_t); return __builtin_bit_cast(unsigned, b); }
; __device__ __forceinline__ float bflo(unsigned w) { return __uint_as_float(w << 16); }
; __device__ __forceinline__ float bfhi(unsigned w) { return __uint_as_float(w & 0xffff0000u); }
; __device__ __forceinline__ float sigm(float x) { return __builtin_amdgcn_rcpf(1.0f + __expf(-x)); }
;     __device__ __forceinline__ void operator()(AccRef acc, const pg8::Unit& u, int, int, int, int) const {
;     ...
;                 for (int bj = 0; bj < 2; ++bj) {
;                     const size_t off = (size_t)row * DM + col0 + bj * 128;
;                     f32x4 h0, h1; const f32x4 a0 = acc[ai][bj][m][0], a1 = acc[ai][bj][m][1];
;                     if (hin) { h0 = *(const f32x4*)(hin + off); h1 = *(const f32x4*)(hin + off + 4); }
;                     else { const v4u hw = *(const v4u*)(hinb + off); h0 = (f32x4){bflo(hw.x), bfhi(hw.x), bflo(hw.y), bfhi(hw.y)}; h1 = (f32x4){bflo(hw.z), bfhi(hw.z), bflo(hw.w), bfhi(hw.w)}; }
;                     if (MODE == 0) { h0 = h0 + a0 * alpha; h1 = h1 + a1 * alpha; }
;                     else { const v4u pw = *(const v4u*)(pp + off);
;                         h0[0] += sigm(a0[0] * rs) * bflo(pw.x); h0[1] += sigm(a0[1] * rs) * bfhi(pw.x); h0[2] += sigm(a0[2] * rs) * bflo(pw.y); h0[3] += sigm(a0[3] * rs) * bfhi(pw.y);
;                         h1[0] += sigm(a1[0] * rs) * bflo(pw.z); h1[1] += sigm(a1[1] * rs) * bfhi(pw.z); h1[2] += sigm(a1[2] * rs) * bflo(pw.w); h1[3] += sigm(a1[3] * rs) * bfhi(pw.w); }
;                     if (hout) { *(f32x4*)(hout + off) = h0; *(f32x4*)(hout + off + 4) = h1; }
;                     if (hb) { v4u w; w.x = cvt_pk_bf16(h0[0], h0[1]); w.y = cvt_pk_bf16(h0[2], h0[3]); w.z = cvt_pk_bf16(h1[0], h1[1]); w.w = cvt_pk_bf16(h1[2], h1[3]); *(v4u*)(hb + off) = w; }
.LBB0_255:
	s_or_b64 exec, exec, s[24:25]
	v_add_u32_e32 v34, 0xa0, v142
	s_waitcnt lgkmcnt(0)
	v_ashrrev_i32_e32 v35, 31, v34
	v_lshlrev_b64 v[36:37], 10, v[34:35]
	v_readlane_b32 s4, v254, 45
	v_lshl_add_u64 v[36:37], v[36:37], 0, v[140:141]
	v_readlane_b32 s5, v254, 46
	s_and_b64 vcc, exec, s[10:11]
	s_nop 0
	v_lshl_add_u64 v[36:37], v[36:37], 1, s[4:5]
	v_lshlrev_b32_e32 v42, 16, v228
	v_and_b32_e32 v43, 0xffff0000, v228
	v_lshlrev_b32_e32 v38, 16, v229
	v_and_b32_e32 v39, 0xffff0000, v229
	v_lshlrev_b32_e32 v44, 16, v230
	v_and_b32_e32 v45, 0xffff0000, v230
	v_lshlrev_b32_e32 v40, 16, v231
	v_and_b32_e32 v41, 0xffff0000, v231
	v_pk_fma_f32 v[32:33], v[32:33], 0.5, v[38:39] op_sel_hi:[1,0,1]
	v_pk_fma_f32 v[30:31], v[30:31], 0.5, v[42:43] op_sel_hi:[1,0,1]
	v_pk_fma_f32 v[28:29], v[28:29], 0.5, v[40:41] op_sel_hi:[1,0,1]
	v_pk_fma_f32 v[26:27], v[26:27], 0.5, v[44:45] op_sel_hi:[1,0,1]
	s_cbranch_vccnz .LBB0_257
	v_cvt_pk_bf16_f32 v38, v30, v31
	v_cvt_pk_bf16_f32 v39, v32, v33
	v_cvt_pk_bf16_f32 v40, v26, v27
	v_cvt_pk_bf16_f32 v41, v28, v29
	global_store_dwordx4 v[36:37], v[38:41], off
.LBB0_257:
	s_and_b64 vcc, exec, s[10:11]
	v_lshlrev_b32_e32 v42, 16, v232
	v_and_b32_e32 v43, 0xffff0000, v232
	v_lshlrev_b32_e32 v38, 16, v233
	v_and_b32_e32 v39, 0xffff0000, v233
	v_lshlrev_b32_e32 v44, 16, v234
	v_and_b32_e32 v45, 0xffff0000, v234
	v_lshlrev_b32_e32 v40, 16, v235
	v_and_b32_e32 v41, 0xffff0000, v235
	v_pk_fma_f32 v[24:25], v[24:25], 0.5, v[38:39] op_sel_hi:[1,0,1]
	v_pk_fma_f32 v[22:23], v[22:23], 0.5, v[42:43] op_sel_hi:[1,0,1]
	v_pk_fma_f32 v[20:21], v[20:21], 0.5, v[40:41] op_sel_hi:[1,0,1]
	v_pk_fma_f32 v[18:19], v[18:19], 0.5, v[44:45] op_sel_hi:[1,0,1]
	s_cbranch_vccnz .LBB0_259
	v_cvt_pk_bf16_f32 v38, v22, v23
	v_cvt_pk_bf16_f32 v39, v24, v25
	v_cvt_pk_bf16_f32 v40, v18, v19
	v_cvt_pk_bf16_f32 v41, v20, v21
	global_store_dwordx4 v[36:37], v[38:41], off offset:256

; __device__ __forceinline__ unsigned cvt_pk_bf16(float lo, float hi) { f32x2_t v = {lo, hi}; bf16x2_t b = __builtin_convertvector(v, bf16x2_t); return __builtin_bit_cast(unsigned, b); }
; __device__ __forceinline__ float bflo(unsigned w) { return __uint_as_float(w << 16); }
; __device__ __forceinline__ float bfhi(unsigned w) { return __uint_as_float(w & 0xffff0000u); }
; __device__ __forceinline__ float sigm(float x) { return __builtin_amdgcn_rcpf(1.0f + __expf(-x)); }
;     __device__ __forceinline__ void operator()(AccRef acc, const pg8::Unit& u, int, int, int, int) const {
;     ...
;                 for (int bj = 0; bj < 2; ++bj) {
;                     const size_t off = (size_t)row * DM + col0 + bj * 128;
;                     f32x4 h0, h1; const f32x4 a0 = acc[ai][bj][m][0], a1 = acc[ai][bj][m][1];
;                     if (hin) { h0 = *(const f32x4*)(hin + off); h1 = *(const f32x4*)(hin + off + 4); }
;                     else { const v4u hw = *(const v4u*)(hinb + off); h0 = (f32x4){bflo(hw.x), bfhi(hw.x), bflo(hw.y), bfhi(hw.y)}; h1 = (f32x4){bflo(hw.z), bfhi(hw.z), bflo(hw.w), bfhi(hw.w)}; }
;                     if (MODE == 0) { h0 = h0 + a0 * alpha; h1 = h1 + a1 * alpha; }
;                     else { const v4u pw = *(const v4u*)(pp + off);
;                         h0[0] += sigm(a0[0] * rs) * bflo(pw.x); h0[1] += sigm(a0[1] * rs) * bfhi(pw.x); h0[2] += sigm(a0[2] * rs) * bflo(pw.y); h0[3] += sigm(a0[3] * rs) * bfhi(pw.y);
;                         h1[0] += sigm(a1[0] * rs) * bflo(pw.z); h1[1] += sigm(a1[1] * rs) * bfhi(pw.z); h1[2] += sigm(a1[2] * rs) * bflo(pw.w); h1[3] += sigm(a1[3] * rs) * bfhi(pw.w); }
;                     if (hout) { *(f32x4*)(hout + off) = h0; *(f32x4*)(hout + off + 4) = h1; }
;                     if (hb) { v4u w; w.x = cvt_pk_bf16(h0[0], h0[1]); w.y = cvt_pk_bf16(h0[2], h0[3]); w.z = cvt_pk_bf16(h1[0], h1[1]); w.w = cvt_pk_bf16(h1[2], h1[3]); *(v4u*)(hb + off) = w; }
.LBB0_261:
	s_or_b64 exec, exec, s[24:25]
	v_add_u32_e32 v18, 0xb0, v142
	s_waitcnt lgkmcnt(0)
	v_ashrrev_i32_e32 v19, 31, v18
	v_lshlrev_b64 v[20:21], 10, v[18:19]
	v_readlane_b32 s4, v254, 45
	v_lshl_add_u64 v[20:21], v[20:21], 0, v[140:141]
	v_readlane_b32 s5, v254, 46
	s_and_b64 vcc, exec, s[10:11]
	s_nop 0
	v_lshl_add_u64 v[20:21], v[20:21], 1, s[4:5]
	v_lshlrev_b32_e32 v26, 16, v236
	v_and_b32_e32 v27, 0xffff0000, v236
	v_lshlrev_b32_e32 v22, 16, v237
	v_and_b32_e32 v23, 0xffff0000, v237
	v_lshlrev_b32_e32 v28, 16, v238
	v_and_b32_e32 v29, 0xffff0000, v238
	v_lshlrev_b32_e32 v24, 16, v239
	v_and_b32_e32 v25, 0xffff0000, v239
	v_pk_fma_f32 v[16:17], v[16:17], 0.5, v[22:23] op_sel_hi:[1,0,1]
	v_pk_fma_f32 v[14:15], v[14:15], 0.5, v[26:27] op_sel_hi:[1,0,1]
	v_pk_fma_f32 v[12:13], v[12:13], 0.5, v[24:25] op_sel_hi:[1,0,1]
	v_pk_fma_f32 v[10:11], v[10:11], 0.5, v[28:29] op_sel_hi:[1,0,1]
	s_cbranch_vccnz .LBB0_263
	v_cvt_pk_bf16_f32 v22, v14, v15
	v_cvt_pk_bf16_f32 v23, v16, v17
	v_cvt_pk_bf16_f32 v24, v10, v11
	v_cvt_pk_bf16_f32 v25, v12, v13
	global_store_dwordx4 v[20:21], v[22:25], off
.LBB0_263:
	s_and_b64 vcc, exec, s[10:11]
	v_lshlrev_b32_e32 v26, 16, v240
	v_and_b32_e32 v27, 0xffff0000, v240
	v_lshlrev_b32_e32 v22, 16, v241
	v_and_b32_e32 v23, 0xffff0000, v241
	v_lshlrev_b32_e32 v28, 16, v242
	v_and_b32_e32 v29, 0xffff0000, v242
	v_lshlrev_b32_e32 v24, 16, v243
	v_and_b32_e32 v25, 0xffff0000, v243
	v_pk_fma_f32 v[8:9], v[8:9], 0.5, v[22:23] op_sel_hi:[1,0,1]
	v_pk_fma_f32 v[6:7], v[6:7], 0.5, v[26:27] op_sel_hi:[1,0,1]
	v_pk_fma_f32 v[4:5], v[4:5], 0.5, v[24:25] op_sel_hi:[1,0,1]
	v_pk_fma_f32 v[2:3], v[2:3], 0.5, v[28:29] op_sel_hi:[1,0,1]
	s_cbranch_vccnz .LBB0_265
	v_cvt_pk_bf16_f32 v22, v6, v7
	v_cvt_pk_bf16_f32 v23, v8, v9
	v_cvt_pk_bf16_f32 v24, v2, v3
	v_cvt_pk_bf16_f32 v25, v4, v5
	global_store_dwordx4 v[20:21], v[22:25], off offset:256

; #define LAS __attribute__((address_space(3)))
; __device__ __forceinline__ unsigned cvt_pk_bf16(float lo, float hi) { f32x2_t v = {lo, hi}; bf16x2_t b = __builtin_convertvector(v, bf16x2_t); return __builtin_bit_cast(unsigned, b); }
; __device__ __forceinline__ float bflo(unsigned w) { return __uint_as_float(w << 16); }
; __device__ __forceinline__ float bfhi(unsigned w) { return __uint_as_float(w & 0xffff0000u); }
;     __device__ __forceinline__ void operator()(AccRef acc, const pg8::Unit& u, int, int, int, int) const {
;     ...
;         for (int ai = 0; ai < 2; ++ai)
; #pragma unroll
;             for (int m = 0; m < 4; ++m) {
;                 const int row = row0 + ai * 128 + m * 16; float ss = 0.f; float rs = 1.f;
;                 if (MODE == 1) rs = ((const LAS float*)((LAS unsigned char*)g_lds + pg8::RSL_OFF))[wid * 128 + ai * 64 + m * 16 + fr];
; #pragma unroll
;                 for (int bj = 0; bj < 2; ++bj) {
;                     const size_t off = (size_t)row * DM + col0 + bj * 128;
;                     f32x4 h0, h1; const f32x4 a0 = acc[ai][bj][m][0], a1 = acc[ai][bj][m][1];
;                     if (hin) { h0 = *(const f32x4*)(hin + off); h1 = *(const f32x4*)(hin + off + 4); }
;                     else { const v4u hw = *(const v4u*)(hinb + off); h0 = (f32x4){bflo(hw.x), bfhi(hw.x), bflo(hw.y), bfhi(hw.y)}; h1 = (f32x4){bflo(hw.z), bfhi(hw.z), bflo(hw.w), bfhi(hw.w)}; }
;                     if (MODE == 0) { h0 = h0 + a0 * alpha; h1 = h1 + a1 * alpha; }
;                     else { const v4u pw = *(const v4u*)(pp + off);
;                         h0[0] += sigm(a0[0] * rs) * bflo(pw.x); h0[1] += sigm(a0[1] * rs) * bfhi(pw.x); h0[2] += sigm(a0[2] * rs) * bflo(pw.y); h0[3] += sigm(a0[3] * rs) * bfhi(pw.y);
;                         h1[0] += sigm(a1[0] * rs) * bflo(pw.z); h1[1] += sigm(a1[1] * rs) * bfhi(pw.z); h1[2] += sigm(a1[2] * rs) * bflo(pw.w); h1[3] += sigm(a1[3] * rs) * bfhi(pw.w); }
;                     if (hout) { *(f32x4*)(hout + off) = h0; *(f32x4*)(hout + off + 4) = h1; }
;                     if (hb) { v4u w; w.x = cvt_pk_bf16(h0[0], h0[1]); w.y = cvt_pk_bf16(h0[2], h0[3]); w.z = cvt_pk_bf16(h1[0], h1[1]); w.w = cvt_pk_bf16(h1[2], h1[3]); *(v4u*)(hb + off) = w; }
;                     ss += ((h0[0] * h0[0] + h0[1] * h0[1]) + (h0[2] * h0[2] + h0[3] * h0[3])) + ((h1[0] * h1[0] + h1[1] * h1[1]) + (h1[2] * h1[2] + h1[3] * h1[3])); }
.LBB0_341:
	v_mov_b32_e32 v141, v155
	s_lshl_b32 s4, s4, 8
	v_readfirstlane_b32 s8, v141
	s_bfe_u32 s15, s8, 0x20006
	s_ashr_i32 s8, s8, 2
	v_bfe_u32 v148, v141, 4, 2
	s_andn2_b32 s8, s8, 63
	s_lshl_b32 s9, s20, 8
	s_lshl_b32 s10, s15, 5
	v_and_or_b32 v141, v141, 15, s4
	s_or_b32 s9, s10, s9
	v_add_u32_e32 v142, s8, v141
	v_lshl_or_b32 v140, v148, 3, s9
	v_ashrrev_i32_e32 v143, 31, v142
	v_ashrrev_i32_e32 v141, 31, v140
	v_lshlrev_b64 v[144:145], 10, v[142:143]
	v_readlane_b32 s4, v254, 45
	v_lshl_add_u64 v[144:145], v[144:145], 0, v[140:141]
	v_readlane_b32 s5, v254, 46
	v_cndmask_b32_e64 v149, 0, 1, s[12:13]
	v_cmp_ne_u32_e64 s[8:9], 1, v149
	v_lshl_add_u64 v[144:145], v[144:145], 1, s[4:5]
	global_load_dwordx4 v[180:183], v[144:145], off
	global_load_dwordx4 v[184:187], v[144:145], off offset:256
	v_add_co_u32_e32 v246, vcc, 0x8000, v144
	s_nop 1
	v_addc_co_u32_e32 v247, vcc, 0, v145, vcc
	global_load_dwordx4 v[188:191], v[246:247], off
	global_load_dwordx4 v[192:195], v[246:247], off offset:256
	v_add_co_u32_e32 v244, vcc, 0x10000, v144
	s_nop 1
	v_addc_co_u32_e32 v245, vcc, 0, v145, vcc
	global_load_dwordx4 v[196:199], v[244:245], off
	global_load_dwordx4 v[200:203], v[244:245], off offset:256
	v_add_co_u32_e32 v246, vcc, 0x18000, v144
	s_nop 1
	v_addc_co_u32_e32 v247, vcc, 0, v145, vcc
	global_load_dwordx4 v[204:207], v[246:247], off
	global_load_dwordx4 v[208:211], v[246:247], off offset:256
	v_add_co_u32_e32 v244, vcc, 0x40000, v144
	s_nop 1
	v_addc_co_u32_e32 v245, vcc, 0, v145, vcc
	global_load_dwordx4 v[212:215], v[244:245], off
	global_load_dwordx4 v[216:219], v[244:245], off offset:256
	v_add_co_u32_e32 v246, vcc, 0x48000, v144
	s_nop 1
	v_addc_co_u32_e32 v247, vcc, 0, v145, vcc
	global_load_dwordx4 v[220:223], v[246:247], off
	global_load_dwordx4 v[224:227], v[246:247], off offset:256
	v_add_co_u32_e32 v244, vcc, 0x50000, v144
	s_nop 1
	v_addc_co_u32_e32 v245, vcc, 0, v145, vcc
	global_load_dwordx4 v[228:231], v[244:245], off
	global_load_dwordx4 v[232:235], v[244:245], off offset:256
	v_add_co_u32_e32 v246, vcc, 0x58000, v144
	s_nop 1
	v_addc_co_u32_e32 v247, vcc, 0, v145, vcc
	global_load_dwordx4 v[236:239], v[246:247], off
	global_load_dwordx4 v[240:243], v[246:247], off offset:256
	s_waitcnt vmcnt(0)
	s_andn2_b64 vcc, exec, s[12:13]
	v_lshlrev_b32_e32 v156, 16, v180
	v_and_b32_e32 v157, 0xffff0000, v180
	v_lshlrev_b32_e32 v150, 16, v181
	v_and_b32_e32 v151, 0xffff0000, v181
	v_lshlrev_b32_e32 v158, 16, v182
	v_and_b32_e32 v159, 0xffff0000, v182
	v_lshlrev_b32_e32 v152, 16, v183
	v_and_b32_e32 v153, 0xffff0000, v183
	v_pk_add_f32 v[128:129], v[128:129], v[150:151]
	v_pk_add_f32 v[126:127], v[126:127], v[156:157]
	v_pk_add_f32 v[124:125], v[124:125], v[152:153]
	v_pk_add_f32 v[122:123], v[122:123], v[158:159]
	s_cbranch_vccnz .LBB0_343
	v_cvt_pk_bf16_f32 v150, v126, v127
	v_cvt_pk_bf16_f32 v151, v128, v129
	v_cvt_pk_bf16_f32 v152, v122, v123
	v_cvt_pk_bf16_f32 v153, v124, v125
	global_store_dwordx4 v[144:145], v[150:153], off
.LBB0_343:
	s_and_b64 vcc, exec, s[8:9]
	v_lshlrev_b32_e32 v156, 16, v184
	v_and_b32_e32 v157, 0xffff0000, v184
	v_lshlrev_b32_e32 v150, 16, v185
	v_and_b32_e32 v151, 0xffff0000, v185
	v_lshlrev_b32_e32 v158, 16, v186
	v_and_b32_e32 v159, 0xffff0000, v186
	v_lshlrev_b32_e32 v152, 16, v187
	v_and_b32_e32 v153, 0xffff0000, v187
	v_pk_add_f32 v[120:121], v[120:121], v[150:151]
	v_pk_add_f32 v[118:119], v[118:119], v[156:157]
	v_pk_add_f32 v[116:117], v[116:117], v[152:153]
	v_pk_add_f32 v[114:115], v[114:115], v[158:159]
	s_cbranch_vccnz .LBB0_345
	v_cvt_pk_bf16_f32 v150, v118, v119
	v_cvt_pk_bf16_f32 v151, v120, v121
	v_cvt_pk_bf16_f32 v152, v114, v115
	v_cvt_pk_bf16_f32 v153, v116, v117
	global_store_dwordx4 v[144:145], v[150:153], off offset:256

; __device__ __forceinline__ unsigned cvt_pk_bf16(float lo, float hi) { f32x2_t v = {lo, hi}; bf16x2_t b = __builtin_convertvector(v, bf16x2_t); return __builtin_bit_cast(unsigned, b); }
; __device__ __forceinline__ float bflo(unsigned w) { return __uint_as_float(w << 16); }
; __device__ __forceinline__ float bfhi(unsigned w) { return __uint_as_float(w & 0xffff0000u); }
; __device__ __forceinline__ float sigm(float x) { return __builtin_amdgcn_rcpf(1.0f + __expf(-x)); }
;     __device__ __forceinline__ void operator()(AccRef acc, const pg8::Unit& u, int, int, int, int) const {
;     ...
;                 for (int bj = 0; bj < 2; ++bj) {
;                     const size_t off = (size_t)row * DM + col0 + bj * 128;
;                     f32x4 h0, h1; const f32x4 a0 = acc[ai][bj][m][0], a1 = acc[ai][bj][m][1];
;                     if (hin) { h0 = *(const f32x4*)(hin + off); h1 = *(const f32x4*)(hin + off + 4); }
;                     else { const v4u hw = *(const v4u*)(hinb + off); h0 = (f32x4){bflo(hw.x), bfhi(hw.x), bflo(hw.y), bfhi(hw.y)}; h1 = (f32x4){bflo(hw.z), bfhi(hw.z), bflo(hw.w), bfhi(hw.w)}; }
;                     if (MODE == 0) { h0 = h0 + a0 * alpha; h1 = h1 + a1 * alpha; }
;                     else { const v4u pw = *(const v4u*)(pp + off);
;                         h0[0] += sigm(a0[0] * rs) * bflo(pw.x); h0[1] += sigm(a0[1] * rs) * bfhi(pw.x); h0[2] += sigm(a0[2] * rs) * bflo(pw.y); h0[3] += sigm(a0[3] * rs) * bfhi(pw.y);
;                         h1[0] += sigm(a1[0] * rs) * bflo(pw.z); h1[1] += sigm(a1[1] * rs) * bfhi(pw.z); h1[2] += sigm(a1[2] * rs) * bflo(pw.w); h1[3] += sigm(a1[3] * rs) * bfhi(pw.w); }
;                     if (hout) { *(f32x4*)(hout + off) = h0; *(f32x4*)(hout + off + 4) = h1; }
;                     if (hb) { v4u w; w.x = cvt_pk_bf16(h0[0], h0[1]); w.y = cvt_pk_bf16(h0[2], h0[3]); w.z = cvt_pk_bf16(h1[0], h1[1]); w.w = cvt_pk_bf16(h1[2], h1[3]); *(v4u*)(hb + off) = w; }
.LBB0_347:
	s_or_b64 exec, exec, s[22:23]
	v_or_b32_e32 v114, 16, v142
	s_waitcnt lgkmcnt(0)
	v_ashrrev_i32_e32 v115, 31, v114
	v_lshlrev_b64 v[116:117], 10, v[114:115]
	v_readlane_b32 s4, v254, 45
	v_lshl_add_u64 v[116:117], v[116:117], 0, v[140:141]
	v_readlane_b32 s5, v254, 46
	s_and_b64 vcc, exec, s[8:9]
	s_nop 0
	v_lshl_add_u64 v[116:117], v[116:117], 1, s[4:5]
	v_lshlrev_b32_e32 v120, 16, v188
	v_and_b32_e32 v121, 0xffff0000, v188
	v_lshlrev_b32_e32 v124, 16, v189
	v_and_b32_e32 v125, 0xffff0000, v189
	v_lshlrev_b32_e32 v128, 16, v190
	v_and_b32_e32 v129, 0xffff0000, v190
	v_lshlrev_b32_e32 v126, 16, v191
	v_and_b32_e32 v127, 0xffff0000, v191
	v_pk_add_f32 v[112:113], v[112:113], v[124:125]
	v_pk_add_f32 v[110:111], v[110:111], v[120:121]
	v_pk_add_f32 v[108:109], v[108:109], v[126:127]
	v_pk_add_f32 v[106:107], v[106:107], v[128:129]
	s_cbranch_vccnz .LBB0_349
	v_cvt_pk_bf16_f32 v124, v110, v111
	v_cvt_pk_bf16_f32 v125, v112, v113
	v_cvt_pk_bf16_f32 v126, v106, v107
	v_cvt_pk_bf16_f32 v127, v108, v109
	global_store_dwordx4 v[116:117], v[124:127], off
.LBB0_349:
	s_and_b64 vcc, exec, s[8:9]
	v_lshlrev_b32_e32 v120, 16, v192
	v_and_b32_e32 v121, 0xffff0000, v192
	v_lshlrev_b32_e32 v124, 16, v193
	v_and_b32_e32 v125, 0xffff0000, v193
	v_lshlrev_b32_e32 v128, 16, v194
	v_and_b32_e32 v129, 0xffff0000, v194
	v_lshlrev_b32_e32 v126, 16, v195
	v_and_b32_e32 v127, 0xffff0000, v195
	v_pk_add_f32 v[104:105], v[104:105], v[124:125]
	v_pk_add_f32 v[102:103], v[102:103], v[120:121]
	v_pk_add_f32 v[100:101], v[100:101], v[126:127]
	v_pk_add_f32 v[98:99], v[98:99], v[128:129]
	s_cbranch_vccnz .LBB0_351
	v_cvt_pk_bf16_f32 v124, v102, v103
	v_cvt_pk_bf16_f32 v125, v104, v105
	v_cvt_pk_bf16_f32 v126, v98, v99
	v_cvt_pk_bf16_f32 v127, v100, v101
	global_store_dwordx4 v[116:117], v[124:127], off offset:256

; __device__ __forceinline__ unsigned cvt_pk_bf16(float lo, float hi) { f32x2_t v = {lo, hi}; bf16x2_t b = __builtin_convertvector(v, bf16x2_t); return __builtin_bit_cast(unsigned, b); }
; __device__ __forceinline__ float bflo(unsigned w) { return __uint_as_float(w << 16); }
; __device__ __forceinline__ float bfhi(unsigned w) { return __uint_as_float(w & 0xffff0000u); }
; __device__ __forceinline__ float sigm(float x) { return __builtin_amdgcn_rcpf(1.0f + __expf(-x)); }
;     __device__ __forceinline__ void operator()(AccRef acc, const pg8::Unit& u, int, int, int, int) const {
;     ...
;                 for (int bj = 0; bj < 2; ++bj) {
;                     const size_t off = (size_t)row * DM + col0 + bj * 128;
;                     f32x4 h0, h1; const f32x4 a0 = acc[ai][bj][m][0], a1 = acc[ai][bj][m][1];
;                     if (hin) { h0 = *(const f32x4*)(hin + off); h1 = *(const f32x4*)(hin + off + 4); }
;                     else { const v4u hw = *(const v4u*)(hinb + off); h0 = (f32x4){bflo(hw.x), bfhi(hw.x), bflo(hw.y), bfhi(hw.y)}; h1 = (f32x4){bflo(hw.z), bfhi(hw.z), bflo(hw.w), bfhi(hw.w)}; }
;                     if (MODE == 0) { h0 = h0 + a0 * alpha; h1 = h1 + a1 * alpha; }
;                     else { const v4u pw = *(const v4u*)(pp + off);
;                         h0[0] += sigm(a0[0] * rs) * bflo(pw.x); h0[1] += sigm(a0[1] * rs) * bfhi(pw.x); h0[2] += sigm(a0[2] * rs) * bflo(pw.y); h0[3] += sigm(a0[3] * rs) * bfhi(pw.y);
;                         h1[0] += sigm(a1[0] * rs) * bflo(pw.z); h1[1] += sigm(a1[1] * rs) * bfhi(pw.z); h1[2] += sigm(a1[2] * rs) * bflo(pw.w); h1[3] += sigm(a1[3] * rs) * bfhi(pw.w); }
;                     if (hout) { *(f32x4*)(hout + off) = h0; *(f32x4*)(hout + off + 4) = h1; }
;                     if (hb) { v4u w; w.x = cvt_pk_bf16(h0[0], h0[1]); w.y = cvt_pk_bf16(h0[2], h0[3]); w.z = cvt_pk_bf16(h1[0], h1[1]); w.w = cvt_pk_bf16(h1[2], h1[3]); *(v4u*)(hb + off) = w; }
.LBB0_353:
	s_or_b64 exec, exec, s[22:23]
	v_or_b32_e32 v98, 32, v142
	s_waitcnt lgkmcnt(0)
	v_ashrrev_i32_e32 v99, 31, v98
	v_lshlrev_b64 v[100:101], 10, v[98:99]
	v_readlane_b32 s4, v254, 45
	v_lshl_add_u64 v[100:101], v[100:101], 0, v[140:141]
	v_readlane_b32 s5, v254, 46
	s_and_b64 vcc, exec, s[8:9]
	s_nop 0
	v_lshl_add_u64 v[100:101], v[100:101], 1, s[4:5]
	v_lshlrev_b32_e32 v106, 16, v196
	v_and_b32_e32 v107, 0xffff0000, v196
	v_lshlrev_b32_e32 v102, 16, v197
	v_and_b32_e32 v103, 0xffff0000, v197
	v_lshlrev_b32_e32 v108, 16, v198
	v_and_b32_e32 v109, 0xffff0000, v198
	v_lshlrev_b32_e32 v104, 16, v199
	v_and_b32_e32 v105, 0xffff0000, v199
	v_pk_add_f32 v[96:97], v[96:97], v[102:103]
	v_pk_add_f32 v[94:95], v[94:95], v[106:107]
	v_pk_add_f32 v[92:93], v[92:93], v[104:105]
	v_pk_add_f32 v[90:91], v[90:91], v[108:109]
	s_cbranch_vccnz .LBB0_355
	v_cvt_pk_bf16_f32 v102, v94, v95
	v_cvt_pk_bf16_f32 v103, v96, v97
	v_cvt_pk_bf16_f32 v104, v90, v91
	v_cvt_pk_bf16_f32 v105, v92, v93
	global_store_dwordx4 v[100:101], v[102:105], off
.LBB0_355:
	s_and_b64 vcc, exec, s[8:9]
	v_lshlrev_b32_e32 v106, 16, v200
	v_and_b32_e32 v107, 0xffff0000, v200
	v_lshlrev_b32_e32 v102, 16, v201
	v_and_b32_e32 v103, 0xffff0000, v201
	v_lshlrev_b32_e32 v108, 16, v202
	v_and_b32_e32 v109, 0xffff0000, v202
	v_lshlrev_b32_e32 v104, 16, v203
	v_and_b32_e32 v105, 0xffff0000, v203
	v_pk_add_f32 v[88:89], v[88:89], v[102:103]
	v_pk_add_f32 v[86:87], v[86:87], v[106:107]
	v_pk_add_f32 v[84:85], v[84:85], v[104:105]
	v_pk_add_f32 v[82:83], v[82:83], v[108:109]
	s_cbranch_vccnz .LBB0_357
	v_cvt_pk_bf16_f32 v102, v86, v87
	v_cvt_pk_bf16_f32 v103, v88, v89
	v_cvt_pk_bf16_f32 v104, v82, v83
	v_cvt_pk_bf16_f32 v105, v84, v85
	global_store_dwordx4 v[100:101], v[102:105], off offset:256

; __device__ __forceinline__ unsigned cvt_pk_bf16(float lo, float hi) { f32x2_t v = {lo, hi}; bf16x2_t b = __builtin_convertvector(v, bf16x2_t); return __builtin_bit_cast(unsigned, b); }
; __device__ __forceinline__ float bflo(unsigned w) { return __uint_as_float(w << 16); }
; __device__ __forceinline__ float bfhi(unsigned w) { return __uint_as_float(w & 0xffff0000u); }
; __device__ __forceinline__ float sigm(float x) { return __builtin_amdgcn_rcpf(1.0f + __expf(-x)); }
;     __device__ __forceinline__ void operator()(AccRef acc, const pg8::Unit& u, int, int, int, int) const {
;     ...
;                 for (int bj = 0; bj < 2; ++bj) {
;                     const size_t off = (size_t)row * DM + col0 + bj * 128;
;                     f32x4 h0, h1; const f32x4 a0 = acc[ai][bj][m][0], a1 = acc[ai][bj][m][1];
;                     if (hin) { h0 = *(const f32x4*)(hin + off); h1 = *(const f32x4*)(hin + off + 4); }
;                     else { const v4u hw = *(const v4u*)(hinb + off); h0 = (f32x4){bflo(hw.x), bfhi(hw.x), bflo(hw.y), bfhi(hw.y)}; h1 = (f32x4){bflo(hw.z), bfhi(hw.z), bflo(hw.w), bfhi(hw.w)}; }
;                     if (MODE == 0) { h0 = h0 + a0 * alpha; h1 = h1 + a1 * alpha; }
;                     else { const v4u pw = *(const v4u*)(pp + off);
;                         h0[0] += sigm(a0[0] * rs) * bflo(pw.x); h0[1] += sigm(a0[1] * rs) * bfhi(pw.x); h0[2] += sigm(a0[2] * rs) * bflo(pw.y); h0[3] += sigm(a0[3] * rs) * bfhi(pw.y);
;                         h1[0] += sigm(a1[0] * rs) * bflo(pw.z); h1[1] += sigm(a1[1] * rs) * bfhi(pw.z); h1[2] += sigm(a1[2] * rs) * bflo(pw.w); h1[3] += sigm(a1[3] * rs) * bfhi(pw.w); }
;                     if (hout) { *(f32x4*)(hout + off) = h0; *(f32x4*)(hout + off + 4) = h1; }
;                     if (hb) { v4u w; w.x = cvt_pk_bf16(h0[0], h0[1]); w.y = cvt_pk_bf16(h0[2], h0[3]); w.z = cvt_pk_bf16(h1[0], h1[1]); w.w = cvt_pk_bf16(h1[2], h1[3]); *(v4u*)(hb + off) = w; }
.LBB0_359:
	s_or_b64 exec, exec, s[22:23]
	v_or_b32_e32 v82, 48, v142
	s_waitcnt lgkmcnt(0)
	v_ashrrev_i32_e32 v83, 31, v82
	v_lshlrev_b64 v[84:85], 10, v[82:83]
	v_readlane_b32 s4, v254, 45
	v_lshl_add_u64 v[84:85], v[84:85], 0, v[140:141]
	v_readlane_b32 s5, v254, 46
	s_and_b64 vcc, exec, s[8:9]
	s_nop 0
	v_lshl_add_u64 v[84:85], v[84:85], 1, s[4:5]
	v_lshlrev_b32_e32 v90, 16, v204
	v_and_b32_e32 v91, 0xffff0000, v204
	v_lshlrev_b32_e32 v86, 16, v205
	v_and_b32_e32 v87, 0xffff0000, v205
	v_lshlrev_b32_e32 v92, 16, v206
	v_and_b32_e32 v93, 0xffff0000, v206
	v_lshlrev_b32_e32 v88, 16, v207
	v_and_b32_e32 v89, 0xffff0000, v207
	v_pk_add_f32 v[80:81], v[80:81], v[86:87]
	v_pk_add_f32 v[78:79], v[78:79], v[90:91]
	v_pk_add_f32 v[76:77], v[76:77], v[88:89]
	v_pk_add_f32 v[74:75], v[74:75], v[92:93]
	s_cbranch_vccnz .LBB0_361
	v_cvt_pk_bf16_f32 v86, v78, v79
	v_cvt_pk_bf16_f32 v87, v80, v81
	v_cvt_pk_bf16_f32 v88, v74, v75
	v_cvt_pk_bf16_f32 v89, v76, v77
	global_store_dwordx4 v[84:85], v[86:89], off
.LBB0_361:
	s_and_b64 vcc, exec, s[8:9]
	v_lshlrev_b32_e32 v90, 16, v208
	v_and_b32_e32 v91, 0xffff0000, v208
	v_lshlrev_b32_e32 v86, 16, v209
	v_and_b32_e32 v87, 0xffff0000, v209
	v_lshlrev_b32_e32 v92, 16, v210
	v_and_b32_e32 v93, 0xffff0000, v210
	v_lshlrev_b32_e32 v88, 16, v211
	v_and_b32_e32 v89, 0xffff0000, v211
	v_pk_add_f32 v[72:73], v[72:73], v[86:87]
	v_pk_add_f32 v[70:71], v[70:71], v[90:91]
	v_pk_add_f32 v[68:69], v[68:69], v[88:89]
	v_pk_add_f32 v[66:67], v[66:67], v[92:93]
	s_cbranch_vccnz .LBB0_363
	v_cvt_pk_bf16_f32 v86, v70, v71
	v_cvt_pk_bf16_f32 v87, v72, v73
	v_cvt_pk_bf16_f32 v88, v66, v67
	v_cvt_pk_bf16_f32 v89, v68, v69
	global_store_dwordx4 v[84:85], v[86:89], off offset:256

; __device__ __forceinline__ unsigned cvt_pk_bf16(float lo, float hi) { f32x2_t v = {lo, hi}; bf16x2_t b = __builtin_convertvector(v, bf16x2_t); return __builtin_bit_cast(unsigned, b); }
; __device__ __forceinline__ float bflo(unsigned w) { return __uint_as_float(w << 16); }
; __device__ __forceinline__ float bfhi(unsigned w) { return __uint_as_float(w & 0xffff0000u); }
; __device__ __forceinline__ float sigm(float x) { return __builtin_amdgcn_rcpf(1.0f + __expf(-x)); }
;     __device__ __forceinline__ void operator()(AccRef acc, const pg8::Unit& u, int, int, int, int) const {
;     ...
;                 for (int bj = 0; bj < 2; ++bj) {
;                     const size_t off = (size_t)row * DM + col0 + bj * 128;
;                     f32x4 h0, h1; const f32x4 a0 = acc[ai][bj][m][0], a1 = acc[ai][bj][m][1];
;                     if (hin) { h0 = *(const f32x4*)(hin + off); h1 = *(const f32x4*)(hin + off + 4); }
;                     else { const v4u hw = *(const v4u*)(hinb + off); h0 = (f32x4){bflo(hw.x), bfhi(hw.x), bflo(hw.y), bfhi(hw.y)}; h1 = (f32x4){bflo(hw.z), bfhi(hw.z), bflo(hw.w), bfhi(hw.w)}; }
;                     if (MODE == 0) { h0 = h0 + a0 * alpha; h1 = h1 + a1 * alpha; }
;                     else { const v4u pw = *(const v4u*)(pp + off);
;                         h0[0] += sigm(a0[0] * rs) * bflo(pw.x); h0[1] += sigm(a0[1] * rs) * bfhi(pw.x); h0[2] += sigm(a0[2] * rs) * bflo(pw.y); h0[3] += sigm(a0[3] * rs) * bfhi(pw.y);
;                         h1[0] += sigm(a1[0] * rs) * bflo(pw.z); h1[1] += sigm(a1[1] * rs) * bfhi(pw.z); h1[2] += sigm(a1[2] * rs) * bflo(pw.w); h1[3] += sigm(a1[3] * rs) * bfhi(pw.w); }
;                     if (hout) { *(f32x4*)(hout + off) = h0; *(f32x4*)(hout + off + 4) = h1; }
;                     if (hb) { v4u w; w.x = cvt_pk_bf16(h0[0], h0[1]); w.y = cvt_pk_bf16(h0[2], h0[3]); w.z = cvt_pk_bf16(h1[0], h1[1]); w.w = cvt_pk_bf16(h1[2], h1[3]); *(v4u*)(hb + off) = w; }
.LBB0_365:
	s_or_b64 exec, exec, s[22:23]
	v_add_u32_e32 v66, 0x80, v142
	s_waitcnt lgkmcnt(0)
	v_ashrrev_i32_e32 v67, 31, v66
	v_lshlrev_b64 v[68:69], 10, v[66:67]
	v_readlane_b32 s4, v254, 45
	v_lshl_add_u64 v[68:69], v[68:69], 0, v[140:141]
	v_readlane_b32 s5, v254, 46
	s_and_b64 vcc, exec, s[8:9]
	s_nop 0
	v_lshl_add_u64 v[68:69], v[68:69], 1, s[4:5]
	v_lshlrev_b32_e32 v74, 16, v212
	v_and_b32_e32 v75, 0xffff0000, v212
	v_lshlrev_b32_e32 v70, 16, v213
	v_and_b32_e32 v71, 0xffff0000, v213
	v_lshlrev_b32_e32 v76, 16, v214
	v_and_b32_e32 v77, 0xffff0000, v214
	v_lshlrev_b32_e32 v72, 16, v215
	v_and_b32_e32 v73, 0xffff0000, v215
	v_pk_add_f32 v[64:65], v[64:65], v[70:71]
	v_pk_add_f32 v[62:63], v[62:63], v[74:75]
	v_pk_add_f32 v[60:61], v[60:61], v[72:73]
	v_pk_add_f32 v[58:59], v[58:59], v[76:77]
	s_cbranch_vccnz .LBB0_367
	v_cvt_pk_bf16_f32 v70, v62, v63
	v_cvt_pk_bf16_f32 v71, v64, v65
	v_cvt_pk_bf16_f32 v72, v58, v59
	v_cvt_pk_bf16_f32 v73, v60, v61
	global_store_dwordx4 v[68:69], v[70:73], off
.LBB0_367:
	s_and_b64 vcc, exec, s[8:9]
	v_lshlrev_b32_e32 v74, 16, v216
	v_and_b32_e32 v75, 0xffff0000, v216
	v_lshlrev_b32_e32 v70, 16, v217
	v_and_b32_e32 v71, 0xffff0000, v217
	v_lshlrev_b32_e32 v76, 16, v218
	v_and_b32_e32 v77, 0xffff0000, v218
	v_lshlrev_b32_e32 v72, 16, v219
	v_and_b32_e32 v73, 0xffff0000, v219
	v_pk_add_f32 v[56:57], v[56:57], v[70:71]
	v_pk_add_f32 v[54:55], v[54:55], v[74:75]
	v_pk_add_f32 v[52:53], v[52:53], v[72:73]
	v_pk_add_f32 v[50:51], v[50:51], v[76:77]
	s_cbranch_vccnz .LBB0_369
	v_cvt_pk_bf16_f32 v70, v54, v55
	v_cvt_pk_bf16_f32 v71, v56, v57
	v_cvt_pk_bf16_f32 v72, v50, v51
	v_cvt_pk_bf16_f32 v73, v52, v53
	global_store_dwordx4 v[68:69], v[70:73], off offset:256

; __device__ __forceinline__ unsigned cvt_pk_bf16(float lo, float hi) { f32x2_t v = {lo, hi}; bf16x2_t b = __builtin_convertvector(v, bf16x2_t); return __builtin_bit_cast(unsigned, b); }
; __device__ __forceinline__ float bflo(unsigned w) { return __uint_as_float(w << 16); }
; __device__ __forceinline__ float bfhi(unsigned w) { return __uint_as_float(w & 0xffff0000u); }
; __device__ __forceinline__ float sigm(float x) { return __builtin_amdgcn_rcpf(1.0f + __expf(-x)); }
;     __device__ __forceinline__ void operator()(AccRef acc, const pg8::Unit& u, int, int, int, int) const {
;     ...
;                 for (int bj = 0; bj < 2; ++bj) {
;                     const size_t off = (size_t)row * DM + col0 + bj * 128;
;                     f32x4 h0, h1; const f32x4 a0 = acc[ai][bj][m][0], a1 = acc[ai][bj][m][1];
;                     if (hin) { h0 = *(const f32x4*)(hin + off); h1 = *(const f32x4*)(hin + off + 4); }
;                     else { const v4u hw = *(const v4u*)(hinb + off); h0 = (f32x4){bflo(hw.x), bfhi(hw.x), bflo(hw.y), bfhi(hw.y)}; h1 = (f32x4){bflo(hw.z), bfhi(hw.z), bflo(hw.w), bfhi(hw.w)}; }
;                     if (MODE == 0) { h0 = h0 + a0 * alpha; h1 = h1 + a1 * alpha; }
;                     else { const v4u pw = *(const v4u*)(pp + off);
;                         h0[0] += sigm(a0[0] * rs) * bflo(pw.x); h0[1] += sigm(a0[1] * rs) * bfhi(pw.x); h0[2] += sigm(a0[2] * rs) * bflo(pw.y); h0[3] += sigm(a0[3] * rs) * bfhi(pw.y);
;                         h1[0] += sigm(a1[0] * rs) * bflo(pw.z); h1[1] += sigm(a1[1] * rs) * bfhi(pw.z); h1[2] += sigm(a1[2] * rs) * bflo(pw.w); h1[3] += sigm(a1[3] * rs) * bfhi(pw.w); }
;                     if (hout) { *(f32x4*)(hout + off) = h0; *(f32x4*)(hout + off + 4) = h1; }
;                     if (hb) { v4u w; w.x = cvt_pk_bf16(h0[0], h0[1]); w.y = cvt_pk_bf16(h0[2], h0[3]); w.z = cvt_pk_bf16(h1[0], h1[1]); w.w = cvt_pk_bf16(h1[2], h1[3]); *(v4u*)(hb + off) = w; }
.LBB0_371:
	s_or_b64 exec, exec, s[22:23]
	v_add_u32_e32 v50, 0x90, v142
	s_waitcnt lgkmcnt(0)
	v_ashrrev_i32_e32 v51, 31, v50
	v_lshlrev_b64 v[52:53], 10, v[50:51]
	v_readlane_b32 s4, v254, 45
	v_lshl_add_u64 v[52:53], v[52:53], 0, v[140:141]
	v_readlane_b32 s5, v254, 46
	s_and_b64 vcc, exec, s[8:9]
	s_nop 0
	v_lshl_add_u64 v[52:53], v[52:53], 1, s[4:5]
	v_lshlrev_b32_e32 v58, 16, v220
	v_and_b32_e32 v59, 0xffff0000, v220
	v_lshlrev_b32_e32 v54, 16, v221
	v_and_b32_e32 v55, 0xffff0000, v221
	v_lshlrev_b32_e32 v60, 16, v222
	v_and_b32_e32 v61, 0xffff0000, v222
	v_lshlrev_b32_e32 v56, 16, v223
	v_and_b32_e32 v57, 0xffff0000, v223
	v_pk_add_f32 v[48:49], v[48:49], v[54:55]
	v_pk_add_f32 v[46:47], v[46:47], v[58:59]
	v_pk_add_f32 v[44:45], v[44:45], v[56:57]
	v_pk_add_f32 v[42:43], v[42:43], v[60:61]
	s_cbranch_vccnz .LBB0_373
	v_cvt_pk_bf16_f32 v54, v46, v47
	v_cvt_pk_bf16_f32 v55, v48, v49
	v_cvt_pk_bf16_f32 v56, v42, v43
	v_cvt_pk_bf16_f32 v57, v44, v45
	global_store_dwordx4 v[52:53], v[54:57], off
.LBB0_373:
	s_and_b64 vcc, exec, s[8:9]
	v_lshlrev_b32_e32 v58, 16, v224
	v_and_b32_e32 v59, 0xffff0000, v224
	v_lshlrev_b32_e32 v54, 16, v225
	v_and_b32_e32 v55, 0xffff0000, v225
	v_lshlrev_b32_e32 v60, 16, v226
	v_and_b32_e32 v61, 0xffff0000, v226
	v_lshlrev_b32_e32 v56, 16, v227
	v_and_b32_e32 v57, 0xffff0000, v227
	v_pk_add_f32 v[40:41], v[40:41], v[54:55]
	v_pk_add_f32 v[38:39], v[38:39], v[58:59]
	v_pk_add_f32 v[36:37], v[36:37], v[56:57]
	v_pk_add_f32 v[34:35], v[34:35], v[60:61]
	s_cbranch_vccnz .LBB0_375
	v_cvt_pk_bf16_f32 v54, v38, v39
	v_cvt_pk_bf16_f32 v55, v40, v41
	v_cvt_pk_bf16_f32 v56, v34, v35
	v_cvt_pk_bf16_f32 v57, v36, v37
	global_store_dwordx4 v[52:53], v[54:57], off offset:256

; __device__ __forceinline__ unsigned cvt_pk_bf16(float lo, float hi) { f32x2_t v = {lo, hi}; bf16x2_t b = __builtin_convertvector(v, bf16x2_t); return __builtin_bit_cast(unsigned, b); }
; __device__ __forceinline__ float bflo(unsigned w) { return __uint_as_float(w << 16); }
; __device__ __forceinline__ float bfhi(unsigned w) { return __uint_as_float(w & 0xffff0000u); }
; __device__ __forceinline__ float sigm(float x) { return __builtin_amdgcn_rcpf(1.0f + __expf(-x)); }
;     __device__ __forceinline__ void operator()(AccRef acc, const pg8::Unit& u, int, int, int, int) const {
;     ...
;                 for (int bj = 0; bj < 2; ++bj) {
;                     const size_t off = (size_t)row * DM + col0 + bj * 128;
;                     f32x4 h0, h1; const f32x4 a0 = acc[ai][bj][m][0], a1 = acc[ai][bj][m][1];
;                     if (hin) { h0 = *(const f32x4*)(hin + off); h1 = *(const f32x4*)(hin + off + 4); }
;                     else { const v4u hw = *(const v4u*)(hinb + off); h0 = (f32x4){bflo(hw.x), bfhi(hw.x), bflo(hw.y), bfhi(hw.y)}; h1 = (f32x4){bflo(hw.z), bfhi(hw.z), bflo(hw.w), bfhi(hw.w)}; }
;                     if (MODE == 0) { h0 = h0 + a0 * alpha; h1 = h1 + a1 * alpha; }
;                     else { const v4u pw = *(const v4u*)(pp + off);
;                         h0[0] += sigm(a0[0] * rs) * bflo(pw.x); h0[1] += sigm(a0[1] * rs) * bfhi(pw.x); h0[2] += sigm(a0[2] * rs) * bflo(pw.y); h0[3] += sigm(a0[3] * rs) * bfhi(pw.y);
;                         h1[0] += sigm(a1[0] * rs) * bflo(pw.z); h1[1] += sigm(a1[1] * rs) * bfhi(pw.z); h1[2] += sigm(a1[2] * rs) * bflo(pw.w); h1[3] += sigm(a1[3] * rs) * bfhi(pw.w); }
;                     if (hout) { *(f32x4*)(hout + off) = h0; *(f32x4*)(hout + off + 4) = h1; }
;                     if (hb) { v4u w; w.x = cvt_pk_bf16(h0[0], h0[1]); w.y = cvt_pk_bf16(h0[2], h0[3]); w.z = cvt_pk_bf16(h1[0], h1[1]); w.w = cvt_pk_bf16(h1[2], h1[3]); *(v4u*)(hb + off) = w; }
.LBB0_377:
	s_or_b64 exec, exec, s[22:23]
	v_add_u32_e32 v34, 0xa0, v142
	s_waitcnt lgkmcnt(0)
	v_ashrrev_i32_e32 v35, 31, v34
	v_lshlrev_b64 v[36:37], 10, v[34:35]
	v_readlane_b32 s4, v254, 45
	v_lshl_add_u64 v[36:37], v[36:37], 0, v[140:141]
	v_readlane_b32 s5, v254, 46
	s_and_b64 vcc, exec, s[8:9]
	s_nop 0
	v_lshl_add_u64 v[36:37], v[36:37], 1, s[4:5]
	v_lshlrev_b32_e32 v42, 16, v228
	v_and_b32_e32 v43, 0xffff0000, v228
	v_lshlrev_b32_e32 v38, 16, v229
	v_and_b32_e32 v39, 0xffff0000, v229
	v_lshlrev_b32_e32 v44, 16, v230
	v_and_b32_e32 v45, 0xffff0000, v230
	v_lshlrev_b32_e32 v40, 16, v231
	v_and_b32_e32 v41, 0xffff0000, v231
	v_pk_add_f32 v[32:33], v[32:33], v[38:39]
	v_pk_add_f32 v[30:31], v[30:31], v[42:43]
	v_pk_add_f32 v[28:29], v[28:29], v[40:41]
	v_pk_add_f32 v[26:27], v[26:27], v[44:45]
	s_cbranch_vccnz .LBB0_379
	v_cvt_pk_bf16_f32 v38, v30, v31
	v_cvt_pk_bf16_f32 v39, v32, v33
	v_cvt_pk_bf16_f32 v40, v26, v27
	v_cvt_pk_bf16_f32 v41, v28, v29
	global_store_dwordx4 v[36:37], v[38:41], off
.LBB0_379:
	s_and_b64 vcc, exec, s[8:9]
	v_lshlrev_b32_e32 v42, 16, v232
	v_and_b32_e32 v43, 0xffff0000, v232
	v_lshlrev_b32_e32 v38, 16, v233
	v_and_b32_e32 v39, 0xffff0000, v233
	v_lshlrev_b32_e32 v44, 16, v234
	v_and_b32_e32 v45, 0xffff0000, v234
	v_lshlrev_b32_e32 v40, 16, v235
	v_and_b32_e32 v41, 0xffff0000, v235
	v_pk_add_f32 v[24:25], v[24:25], v[38:39]
	v_pk_add_f32 v[22:23], v[22:23], v[42:43]
	v_pk_add_f32 v[20:21], v[20:21], v[40:41]
	v_pk_add_f32 v[18:19], v[18:19], v[44:45]
	s_cbranch_vccnz .LBB0_381
	v_cvt_pk_bf16_f32 v38, v22, v23
	v_cvt_pk_bf16_f32 v39, v24, v25
	v_cvt_pk_bf16_f32 v40, v18, v19
	v_cvt_pk_bf16_f32 v41, v20, v21
	global_store_dwordx4 v[36:37], v[38:41], off offset:256

; __device__ __forceinline__ unsigned cvt_pk_bf16(float lo, float hi) { f32x2_t v = {lo, hi}; bf16x2_t b = __builtin_convertvector(v, bf16x2_t); return __builtin_bit_cast(unsigned, b); }
; __device__ __forceinline__ float bflo(unsigned w) { return __uint_as_float(w << 16); }
; __device__ __forceinline__ float bfhi(unsigned w) { return __uint_as_float(w & 0xffff0000u); }
; __device__ __forceinline__ float sigm(float x) { return __builtin_amdgcn_rcpf(1.0f + __expf(-x)); }
;     __device__ __forceinline__ void operator()(AccRef acc, const pg8::Unit& u, int, int, int, int) const {
;     ...
;                 for (int bj = 0; bj < 2; ++bj) {
;                     const size_t off = (size_t)row * DM + col0 + bj * 128;
;                     f32x4 h0, h1; const f32x4 a0 = acc[ai][bj][m][0], a1 = acc[ai][bj][m][1];
;                     if (hin) { h0 = *(const f32x4*)(hin + off); h1 = *(const f32x4*)(hin + off + 4); }
;                     else { const v4u hw = *(const v4u*)(hinb + off); h0 = (f32x4){bflo(hw.x), bfhi(hw.x), bflo(hw.y), bfhi(hw.y)}; h1 = (f32x4){bflo(hw.z), bfhi(hw.z), bflo(hw.w), bfhi(hw.w)}; }
;                     if (MODE == 0) { h0 = h0 + a0 * alpha; h1 = h1 + a1 * alpha; }
;                     else { const v4u pw = *(const v4u*)(pp + off);
;                         h0[0] += sigm(a0[0] * rs) * bflo(pw.x); h0[1] += sigm(a0[1] * rs) * bfhi(pw.x); h0[2] += sigm(a0[2] * rs) * bflo(pw.y); h0[3] += sigm(a0[3] * rs) * bfhi(pw.y);
;                         h1[0] += sigm(a1[0] * rs) * bflo(pw.z); h1[1] += sigm(a1[1] * rs) * bfhi(pw.z); h1[2] += sigm(a1[2] * rs) * bflo(pw.w); h1[3] += sigm(a1[3] * rs) * bfhi(pw.w); }
;                     if (hout) { *(f32x4*)(hout + off) = h0; *(f32x4*)(hout + off + 4) = h1; }
;                     if (hb) { v4u w; w.x = cvt_pk_bf16(h0[0], h0[1]); w.y = cvt_pk_bf16(h0[2], h0[3]); w.z = cvt_pk_bf16(h1[0], h1[1]); w.w = cvt_pk_bf16(h1[2], h1[3]); *(v4u*)(hb + off) = w; }
.LBB0_383:
	s_or_b64 exec, exec, s[22:23]
	v_add_u32_e32 v18, 0xb0, v142
	s_waitcnt lgkmcnt(0)
	v_ashrrev_i32_e32 v19, 31, v18
	v_lshlrev_b64 v[20:21], 10, v[18:19]
	v_readlane_b32 s4, v254, 45
	v_lshl_add_u64 v[20:21], v[20:21], 0, v[140:141]
	v_readlane_b32 s5, v254, 46
	s_and_b64 vcc, exec, s[8:9]
	s_nop 0
	v_lshl_add_u64 v[20:21], v[20:21], 1, s[4:5]
	v_lshlrev_b32_e32 v26, 16, v236
	v_and_b32_e32 v27, 0xffff0000, v236
	v_lshlrev_b32_e32 v22, 16, v237
	v_and_b32_e32 v23, 0xffff0000, v237
	v_lshlrev_b32_e32 v28, 16, v238
	v_and_b32_e32 v29, 0xffff0000, v238
	v_lshlrev_b32_e32 v24, 16, v239
	v_and_b32_e32 v25, 0xffff0000, v239
	v_pk_add_f32 v[16:17], v[16:17], v[22:23]
	v_pk_add_f32 v[14:15], v[14:15], v[26:27]
	v_pk_add_f32 v[12:13], v[12:13], v[24:25]
	v_pk_add_f32 v[10:11], v[10:11], v[28:29]
	s_cbranch_vccnz .LBB0_385
	v_cvt_pk_bf16_f32 v22, v14, v15
	v_cvt_pk_bf16_f32 v23, v16, v17
	v_cvt_pk_bf16_f32 v24, v10, v11
	v_cvt_pk_bf16_f32 v25, v12, v13
	global_store_dwordx4 v[20:21], v[22:25], off
.LBB0_385:
	s_and_b64 vcc, exec, s[8:9]
	v_lshlrev_b32_e32 v26, 16, v240
	v_and_b32_e32 v27, 0xffff0000, v240
	v_lshlrev_b32_e32 v22, 16, v241
	v_and_b32_e32 v23, 0xffff0000, v241
	v_lshlrev_b32_e32 v28, 16, v242
	v_and_b32_e32 v29, 0xffff0000, v242
	v_lshlrev_b32_e32 v24, 16, v243
	v_and_b32_e32 v25, 0xffff0000, v243
	v_pk_add_f32 v[8:9], v[8:9], v[22:23]
	v_pk_add_f32 v[6:7], v[6:7], v[26:27]
	v_pk_add_f32 v[4:5], v[4:5], v[24:25]
	v_pk_add_f32 v[2:3], v[2:3], v[28:29]
	s_cbranch_vccnz .LBB0_387
	v_cvt_pk_bf16_f32 v22, v6, v7
	v_cvt_pk_bf16_f32 v23, v8, v9
	v_cvt_pk_bf16_f32 v24, v2, v3
	v_cvt_pk_bf16_f32 v25, v4, v5
	global_store_dwordx4 v[20:21], v[22:25], off offset:256
